# transposes (kscale variant): 16 gain loads batched; sgu_mix: 4 weight-tile loads per item batched (both were serialized load/wait chains), on top of v10
# baseline (speedup 1.0000x reference)
; __device__ __forceinline__ void ph_sgu_mix_fast(const bf16* __restrict__ proj, const bf16* __restrict__ VLN, const bf16* __restrict__ WSG, const float* __restrict__ sgu_b, bf16* __restrict__ mix, unsigned* __restrict__ queue) {
;     ...
;         __syncthreads();
;         const int item = (int)*qw;
;         if (item >= BATCH * 32 * 4) break;
;         const int lane = tid & 63, wave = tid >> 6, r16 = lane & 15, a = lane >> 4;
;         const int g = item & 3, n = (item >> 2) & 31, b = item >> 7;
;         const size_t m0 = (size_t)b * SEQ + n * 128;
;         __syncthreads();
; #pragma unroll
;         for (int i = 0; i < 4; ++i) { const int c = tid + 512 * i, s = c >> 4, part = c & 15;
;             *(u32x4*)(lds_dyn + s * SG_STR + part * 16) = *(const u32x4*)(VLN + (m0 + s) * 512 + g * 128 + part * 8); }
;         const int nks = ((16 * wave + 15) >> 5) + 1;
;         bf16x8 wf[4];
; #pragma unroll
;         for (int ks = 0; ks < 4; ++ks) wf[ks] = ld_frag(WSG + ((size_t)g * 128 + 16 * wave + r16) * 128 + 32 * ks + 8 * a);
;         __syncthreads();
.LBB0_1732:
	s_or_b64 exec, exec, s[0:1]
	s_add_i32 s0, 0, 0x8800
	s_cmp_lg_u32 s0, -1
	s_cselect_b32 s0, s0, 0
	s_cselect_b32 s1, s25, 0
	v_mov_b32_e32 v4, s0
	v_mov_b32_e32 v5, s1
	s_waitcnt lgkmcnt(0)
	s_barrier
	flat_load_dword v28, v[4:5] sc0 sc1
	s_waitcnt vmcnt(0)
	s_mov_b64 s[0:1], -1
	s_waitcnt lgkmcnt(0)
	v_cmp_gt_i32_e32 vcc, s77, v28
	s_and_saveexec_b64 s[34:35], vcc
	s_cbranch_execz .LBB0_1727
	v_ashrrev_i32_e32 v4, 7, v28
	v_ashrrev_i32_e32 v5, 31, v4
	v_lshlrev_b64 v[24:25], 12, v[4:5]
	v_lshlrev_b32_e32 v2, 5, v28
	s_movk_i32 s0, 0xf80
	v_and_or_b32 v24, v2, s0, v24
	v_lshlrev_b32_e32 v2, 7, v28
	v_and_b32_e32 v2, 0x180, v2
	v_and_b32_e32 v27, 15, v26
	v_lshlrev_b32_e32 v6, 1, v2
	v_mov_b32_e32 v7, v3
	v_ashrrev_i32_e32 v14, 4, v26
	v_lshl_add_u64 v[6:7], s[12:13], 0, v[6:7]
	v_lshlrev_b32_e32 v22, 4, v27
	v_mov_b32_e32 v23, v3
	v_ashrrev_i32_e32 v15, 31, v14
	v_lshl_add_u64 v[10:11], v[6:7], 0, v[22:23]
	v_lshl_add_u64 v[6:7], v[24:25], 0, v[14:15]
	v_lshlrev_b64 v[6:7], 10, v[6:7]
	v_lshl_add_u64 v[6:7], v[10:11], 0, v[6:7]
	s_barrier
	global_load_dwordx4 v[116:119], v[6:7], off
	v_add_u32_e32 v12, 0, v22
	v_mad_u64_u32 v[132:133], s[0:1], v14, s93, v[12:13]
	v_ashrrev_i32_e32 v23, 2, v26
	v_bfe_u32 v29, v26, 4, 2
	v_bfi_b32 v30, -16, v23, v26
	v_ashrrev_i32_e32 v35, 7, v26
	v_mul_i32_i24_e32 v36, -14, v27
	v_ashrrev_i32_e32 v31, 31, v30
	s_movk_i32 s2, 0x880
	v_lshlrev_b64 v[4:5], 24, v[4:5]
	v_lshlrev_b32_e32 v34, 3, v29
	v_cmp_lt_i32_e64 s[4:5], 0, v35
	v_cmp_lt_i32_e64 s[6:7], 1, v35
	v_cmp_lt_i32_e64 s[8:9], 2, v35
	s_mov_b64 s[36:37], 0
	v_add_u32_e32 v6, 0x200, v26
	v_ashrrev_i32_e32 v14, 4, v6
	v_ashrrev_i32_e32 v15, 31, v14
	v_lshl_add_u64 v[6:7], v[24:25], 0, v[14:15]
	v_lshlrev_b64 v[6:7], 10, v[6:7]
	v_lshl_add_u64 v[6:7], v[10:11], 0, v[6:7]
	global_load_dwordx4 v[120:123], v[6:7], off
	v_mad_u64_u32 v[134:135], s[0:1], v14, s93, v[12:13]
	v_add_u32_e32 v6, 0x400, v26
	v_ashrrev_i32_e32 v14, 4, v6
	v_ashrrev_i32_e32 v15, 31, v14
	v_lshl_add_u64 v[6:7], v[24:25], 0, v[14:15]
	v_lshlrev_b64 v[6:7], 10, v[6:7]
	v_lshl_add_u64 v[6:7], v[10:11], 0, v[6:7]
	global_load_dwordx4 v[124:127], v[6:7], off
	v_mad_u64_u32 v[136:137], s[0:1], v14, s93, v[12:13]
	v_add_u32_e32 v6, 0x600, v26
	v_ashrrev_i32_e32 v14, 4, v6
	v_ashrrev_i32_e32 v15, 31, v14
	v_lshl_add_u64 v[6:7], v[24:25], 0, v[14:15]
	v_lshlrev_b64 v[6:7], 10, v[6:7]
	v_lshl_add_u64 v[6:7], v[10:11], 0, v[6:7]
	global_load_dwordx4 v[128:131], v[6:7], off
	v_mad_u64_u32 v[10:11], s[0:1], v14, s93, v[12:13]
	v_add_u32_e32 v26, v2, v30
	v_lshl_add_u64 v[24:25], v[24:25], 0, v[30:31]
	v_mad_u64_u32 v[32:33], s[0:1], v24, s23, 0
	v_cmp_lt_i32_e64 s[0:1], -1, v35
	s_waitcnt vmcnt(0)
	ds_write_b128 v132, v[116:119]
	ds_write_b128 v134, v[120:123]
	ds_write_b128 v136, v[124:127]
	ds_write_b128 v10, v[128:131]
	v_and_b32_e32 v6, -16, v23
	v_ashrrev_i32_e32 v7, 31, v6
	v_lshl_add_u64 v[6:7], v[2:3], 0, v[6:7]
	v_or_b32_e32 v6, v6, v27
	v_lshlrev_b64 v[6:7], 8, v[6:7]
	v_lshl_add_u64 v[6:7], s[14:15], 0, v[6:7]
	v_lshlrev_b32_e32 v8, 4, v29
	v_mov_b32_e32 v9, v3
	v_lshl_add_u64 v[18:19], v[6:7], 0, v[8:9]
	v_ashrrev_i32_e32 v27, 31, v26
	global_load_dwordx4 v[6:9], v[18:19], off
	global_load_dwordx4 v[10:13], v[18:19], off offset:64
	global_load_dwordx4 v[14:17], v[18:19], off offset:128
	s_nop 0
	global_load_dwordx4 v[18:21], v[18:19], off offset:192
	v_lshl_add_u64 v[26:27], v[26:27], 2, s[16:17]
	s_waitcnt lgkmcnt(0)
	s_barrier
	global_load_dword v26, v[26:27], off
	v_mad_u32_u24 v2, v29, s2, v36
	v_add3_u32 v36, v2, v22, 0
	v_lshlrev_b32_e32 v2, 17, v28
	s_mov_b32 s2, 0xf80000
	v_mad_i32_i24 v23, v25, s23, v33
	v_and_or_b32 v4, v2, s2, v4
	v_lshlrev_b64 v[24:25], 12, v[30:31]
	v_lshlrev_b32_e32 v2, 8, v28
	v_lshl_add_u64 v[4:5], v[4:5], 0, v[24:25]
	v_and_b32_e32 v2, 0x300, v2
	v_or3_b32 v4, v4, v2, v34
	v_or3_b32 v22, v32, v2, v34
	v_lshl_add_u64 v[28:29], s[10:11], 0, v[4:5]
	v_lshl_add_u64 v[30:31], s[10:11], 0, v[22:23]
	s_waitcnt vmcnt(0)
	v_mov_b32_e32 v27, v26
	s_branch .LBB0_1735

;     ...
;     for (int it = it_lo; it < it_hi; it += it_st) {
;         const int kb = it / nblk, nb = it % nblk, k0 = 64 * kb, n0 = 64 * nb;
;         const int ng = n0 + n4; const int no = MAP ? win_map(ng) : ng;
;         const bool vec = MAP ? (no >= 0 && win_map(ng + 3) == no + 3) : true;
;         f32x4 v[16];
;         if (vec) {
; #pragma unroll
;             for (int i = 0; i < 16; ++i) { const float* p = W + (size_t)(k0 + 4 * i + ksub) * N_orig + no; if (MAP) { const f32x2 a0 = *(const f32x2*)p, a1 = *(const f32x2*)(p + 2); v[i] = (f32x4){a0.x, a0.y, a1.x, a1.y}; }
;                 else v[i] = __builtin_nontemporal_load((const f32x4*)p); }
;         } else {
; #pragma unroll
;             for (int i = 0; i < 16; ++i) { const float* p = W + (size_t)(k0 + 4 * i + ksub) * N_orig;
; #pragma unroll
;                 for (int e = 0; e < 4; ++e) { const int ne = MAP ? win_map(ng + e) : ng + e; v[i][e] = ne >= 0 ? p[ne] : 0.f; } }
;         }
;         if (kscale) {
; #pragma unroll
;             for (int i = 0; i < 16; ++i) v[i] *= kscale[k0 + 4 * i + ksub]; }
.LBB0_1888:
	v_ashrrev_i32_e32 v4, 31, v1
	v_lshrrev_b32_e32 v4, 25, v4
	v_add_u32_e32 v4, v1, v4
	v_ashrrev_i32_e32 v4, 7, v4
	v_lshlrev_b32_e32 v70, 6, v4
	v_lshlrev_b32_e32 v71, 13, v4
	v_add_u32_e32 v4, v77, v75
	v_or_b32_e32 v72, v70, v74
	v_sub_u32_e32 v4, v4, v71
	v_or_b32_e32 v6, 4, v72
	v_or_b32_e32 v12, 8, v72
	v_or_b32_e32 v14, 12, v72
	v_or_b32_e32 v20, 16, v72
	v_or_b32_e32 v22, 20, v72
	v_or_b32_e32 v28, 24, v72
	v_or_b32_e32 v30, 28, v72
	v_or_b32_e32 v36, 32, v72
	v_or_b32_e32 v38, 36, v72
	v_or_b32_e32 v44, 40, v72
	v_or_b32_e32 v46, 44, v72
	v_or_b32_e32 v52, 48, v72
	v_or_b32_e32 v54, 52, v72
	v_or_b32_e32 v62, 56, v72
	v_or_b32_e32 v64, 60, v72
	v_ashrrev_i32_e32 v5, 31, v4
	v_ashrrev_i32_e32 v73, 31, v72
	v_ashrrev_i32_e32 v7, 31, v6
	v_ashrrev_i32_e32 v13, 31, v12
	v_ashrrev_i32_e32 v15, 31, v14
	v_ashrrev_i32_e32 v21, 31, v20
	v_ashrrev_i32_e32 v23, 31, v22
	v_ashrrev_i32_e32 v29, 31, v28
	v_ashrrev_i32_e32 v31, 31, v30
	v_ashrrev_i32_e32 v37, 31, v36
	v_ashrrev_i32_e32 v39, 31, v38
	v_ashrrev_i32_e32 v45, 31, v44
	v_ashrrev_i32_e32 v47, 31, v46
	v_ashrrev_i32_e32 v53, 31, v52
	v_ashrrev_i32_e32 v55, 31, v54
	v_ashrrev_i32_e32 v63, 31, v62
	v_ashrrev_i32_e32 v65, 31, v64
	v_lshl_add_u64 v[60:61], v[4:5], 2, s[10:11]
	v_lshlrev_b64 v[4:5], 15, v[72:73]
	v_lshlrev_b64 v[6:7], 15, v[6:7]
	v_lshlrev_b64 v[12:13], 15, v[12:13]
	v_lshlrev_b64 v[14:15], 15, v[14:15]
	v_lshlrev_b64 v[20:21], 15, v[20:21]
	v_lshlrev_b64 v[22:23], 15, v[22:23]
	v_lshlrev_b64 v[28:29], 15, v[28:29]
	v_lshlrev_b64 v[30:31], 15, v[30:31]
	v_lshlrev_b64 v[36:37], 15, v[36:37]
	v_lshlrev_b64 v[38:39], 15, v[38:39]
	v_lshlrev_b64 v[44:45], 15, v[44:45]
	v_lshlrev_b64 v[46:47], 15, v[46:47]
	v_lshlrev_b64 v[52:53], 15, v[52:53]
	v_lshlrev_b64 v[54:55], 15, v[54:55]
	v_lshlrev_b64 v[62:63], 15, v[62:63]
	v_lshlrev_b64 v[64:65], 15, v[64:65]
	v_lshl_add_u64 v[4:5], v[60:61], 0, v[4:5]
	v_lshl_add_u64 v[6:7], v[60:61], 0, v[6:7]
	v_lshl_add_u64 v[12:13], v[60:61], 0, v[12:13]
	v_lshl_add_u64 v[14:15], v[60:61], 0, v[14:15]
	v_lshl_add_u64 v[20:21], v[60:61], 0, v[20:21]
	v_lshl_add_u64 v[22:23], v[60:61], 0, v[22:23]
	v_lshl_add_u64 v[28:29], v[60:61], 0, v[28:29]
	v_lshl_add_u64 v[30:31], v[60:61], 0, v[30:31]
	v_lshl_add_u64 v[36:37], v[60:61], 0, v[36:37]
	v_lshl_add_u64 v[38:39], v[60:61], 0, v[38:39]
	v_lshl_add_u64 v[44:45], v[60:61], 0, v[44:45]
	v_lshl_add_u64 v[46:47], v[60:61], 0, v[46:47]
	v_lshl_add_u64 v[52:53], v[60:61], 0, v[52:53]
	v_lshl_add_u64 v[54:55], v[60:61], 0, v[54:55]
	v_lshl_add_u64 v[62:63], v[60:61], 0, v[62:63]
	v_lshl_add_u64 v[60:61], v[60:61], 0, v[64:65]
	global_load_dwordx4 v[8:11], v[4:5], off nt
	s_nop 0
	global_load_dwordx4 v[4:7], v[6:7], off nt
	s_nop 0
	global_load_dwordx4 v[16:19], v[12:13], off nt
	s_nop 0
	global_load_dwordx4 v[12:15], v[14:15], off nt
	s_nop 0
	global_load_dwordx4 v[24:27], v[20:21], off nt
	s_nop 0
	global_load_dwordx4 v[20:23], v[22:23], off nt
	s_nop 0
	global_load_dwordx4 v[32:35], v[28:29], off nt
	s_nop 0
	global_load_dwordx4 v[28:31], v[30:31], off nt
	s_nop 0
	global_load_dwordx4 v[40:43], v[36:37], off nt
	s_nop 0
	global_load_dwordx4 v[36:39], v[38:39], off nt
	s_nop 0
	global_load_dwordx4 v[48:51], v[44:45], off nt
	s_nop 0
	global_load_dwordx4 v[44:47], v[46:47], off nt
	s_nop 0
	global_load_dwordx4 v[56:59], v[52:53], off nt
	s_nop 0
	global_load_dwordx4 v[52:55], v[54:55], off nt
	s_nop 0
	global_load_dwordx4 v[64:67], v[62:63], off nt
	s_nop 0
	global_load_dwordx4 v[60:63], v[60:61], off nt
	s_andn2_b64 vcc, exec, s[16:17]
	s_cbranch_vccnz .LBB0_1887
	v_lshl_add_u64 v[72:73], v[72:73], 2, s[12:13]
	global_load_dword v116, v[72:73], off
	global_load_dword v118, v[72:73], off offset:16
	global_load_dword v120, v[72:73], off offset:32
	global_load_dword v122, v[72:73], off offset:48
	global_load_dword v124, v[72:73], off offset:64
	global_load_dword v126, v[72:73], off offset:80
	global_load_dword v128, v[72:73], off offset:96
	global_load_dword v130, v[72:73], off offset:112
	global_load_dword v132, v[72:73], off offset:128
	global_load_dword v134, v[72:73], off offset:144
	global_load_dword v136, v[72:73], off offset:160
	global_load_dword v138, v[72:73], off offset:176
	global_load_dword v140, v[72:73], off offset:192
	global_load_dword v142, v[72:73], off offset:208
	global_load_dword v144, v[72:73], off offset:224
	global_load_dword v146, v[72:73], off offset:240
	s_waitcnt vmcnt(0)
	v_pk_mul_f32 v[10:11], v[10:11], v[116:117] op_sel_hi:[1,0]
	v_pk_mul_f32 v[8:9], v[8:9], v[116:117] op_sel_hi:[1,0]
	v_pk_mul_f32 v[6:7], v[6:7], v[118:119] op_sel_hi:[1,0]
	v_pk_mul_f32 v[4:5], v[4:5], v[118:119] op_sel_hi:[1,0]
	v_pk_mul_f32 v[18:19], v[18:19], v[120:121] op_sel_hi:[1,0]
	v_pk_mul_f32 v[16:17], v[16:17], v[120:121] op_sel_hi:[1,0]
	v_pk_mul_f32 v[14:15], v[14:15], v[122:123] op_sel_hi:[1,0]
	v_pk_mul_f32 v[12:13], v[12:13], v[122:123] op_sel_hi:[1,0]
	v_pk_mul_f32 v[26:27], v[26:27], v[124:125] op_sel_hi:[1,0]
	v_pk_mul_f32 v[24:25], v[24:25], v[124:125] op_sel_hi:[1,0]
	v_pk_mul_f32 v[22:23], v[22:23], v[126:127] op_sel_hi:[1,0]
	v_pk_mul_f32 v[20:21], v[20:21], v[126:127] op_sel_hi:[1,0]
	v_pk_mul_f32 v[34:35], v[34:35], v[128:129] op_sel_hi:[1,0]
	v_pk_mul_f32 v[32:33], v[32:33], v[128:129] op_sel_hi:[1,0]
	v_pk_mul_f32 v[30:31], v[30:31], v[130:131] op_sel_hi:[1,0]
	v_pk_mul_f32 v[28:29], v[28:29], v[130:131] op_sel_hi:[1,0]
	v_pk_mul_f32 v[42:43], v[42:43], v[132:133] op_sel_hi:[1,0]
	v_pk_mul_f32 v[40:41], v[40:41], v[132:133] op_sel_hi:[1,0]
	v_pk_mul_f32 v[38:39], v[38:39], v[134:135] op_sel_hi:[1,0]
	v_pk_mul_f32 v[36:37], v[36:37], v[134:135] op_sel_hi:[1,0]
	v_pk_mul_f32 v[50:51], v[50:51], v[136:137] op_sel_hi:[1,0]
	v_pk_mul_f32 v[48:49], v[48:49], v[136:137] op_sel_hi:[1,0]
	v_pk_mul_f32 v[46:47], v[46:47], v[138:139] op_sel_hi:[1,0]
	v_pk_mul_f32 v[44:45], v[44:45], v[138:139] op_sel_hi:[1,0]
	v_pk_mul_f32 v[58:59], v[58:59], v[140:141] op_sel_hi:[1,0]
	v_pk_mul_f32 v[56:57], v[56:57], v[140:141] op_sel_hi:[1,0]
	v_pk_mul_f32 v[54:55], v[54:55], v[142:143] op_sel_hi:[1,0]
	v_pk_mul_f32 v[52:53], v[52:53], v[142:143] op_sel_hi:[1,0]
	v_pk_mul_f32 v[66:67], v[66:67], v[144:145] op_sel_hi:[1,0]
	v_pk_mul_f32 v[64:65], v[64:65], v[144:145] op_sel_hi:[1,0]
	v_pk_mul_f32 v[62:63], v[62:63], v[146:147] op_sel_hi:[1,0]
	v_pk_mul_f32 v[60:61], v[60:61], v[146:147] op_sel_hi:[1,0]
	s_branch .LBB0_1887
